# seams: the early agent-scope acquire is issued after the arrival atomic's result returns (overlaps the L2 write-back / the first poll instead of delaying the last-arriver test)
# baseline (speedup 1.0000x reference)
; __device__ __forceinline__ unsigned xb_ld(unsigned* p)              { return __hip_atomic_load(p, __ATOMIC_RELAXED, __HIP_MEMORY_SCOPE_AGENT); }
; __device__ __forceinline__ unsigned xb_add(unsigned* p, unsigned v) { return __hip_atomic_fetch_add(p, v, __ATOMIC_RELAXED, __HIP_MEMORY_SCOPE_AGENT); }
; #define XB_SPIN(cond, bar) do { unsigned _sp = 0; while (cond) { __builtin_amdgcn_s_sleep(1); \
;     if ((++_sp & 255u) == 0u) { if (xb_ld(&(bar)[XB_TMO])) break; if (_sp > XB_SPIN_CAP) { atomicAdd(&(bar)[XB_TMO], 1u); break; } } } } while (0)
; __device__ __forceinline__ void xcd_barrier(const XcdBarrier& b) {
;     ...
;         const unsigned old = xb_add(&bar[XB_XSUB(b.x)], 1u);
;         const unsigned gen = old / nloc;
;         if (old + 1u == (gen + 1u) * nloc) {
;             __builtin_amdgcn_fence(__ATOMIC_RELEASE, "agent");
;             asm volatile("s_waitcnt vmcnt(0)" ::: "memory");
;             const unsigned og = xb_add(&bar[XB_TOP], 1u);
;             const unsigned tg = og / nx;
;             if (og + 1u == (tg + 1u) * nx) xb_add(&bar[XB_TOPGEN], 1u);
;             else XB_SPIN(xb_ld(&bar[XB_TOPGEN]) == tg, bar);
;             __builtin_amdgcn_fence(__ATOMIC_ACQUIRE, "agent");
;             xb_add(&bar[XB_XGEN(b.x)], 1u);
;             asm volatile("s_waitcnt vmcnt(0)" ::: "memory");
;         } else {
;             XB_SPIN(xb_ld(&bar[XB_XGEN(b.x)]) == gen, bar);
.LBB0_151:
	s_lshl_b32 s6, s65, 8
	v_readlane_b32 s8, v247, 16
	v_readlane_b32 s9, v247, 17
	s_add_u32 s6, s8, s6
	s_addc_u32 s7, s9, 0
	v_mov_b32_e32 v1, 0x1000
	v_mov_b32_e32 v3, 1
	global_atomic_add v3, v1, v3, s[6:7] offset:1024 sc0
	v_cvt_f32_u32_e32 v1, v2
	v_sub_u32_e32 v4, 0, v2
	v_rcp_iflag_f32_e32 v1, v1
	s_nop 0
	v_mul_f32_e32 v1, 0x4f7ffffe, v1
	v_cvt_u32_f32_e32 v1, v1
	v_mul_lo_u32 v4, v4, v1
	v_mul_hi_u32 v4, v1, v4
	v_add_u32_e32 v1, v1, v4
	s_waitcnt vmcnt(0)
	buffer_inv sc1
	v_mul_hi_u32 v1, v3, v1
	v_mul_lo_u32 v4, v1, v2
	v_sub_u32_e32 v4, v3, v4
	v_add_u32_e32 v5, 1, v1
	v_cmp_ge_u32_e32 vcc, v4, v2
	v_add_u32_e32 v3, 1, v3
	s_nop 0
	v_cndmask_b32_e32 v1, v1, v5, vcc
	v_sub_u32_e32 v5, v4, v2
	v_cndmask_b32_e32 v4, v4, v5, vcc
	v_add_u32_e32 v5, 1, v1
	v_cmp_ge_u32_e32 vcc, v4, v2
	s_nop 1
	v_cndmask_b32_e32 v1, v1, v5, vcc
	v_mul_lo_u32 v4, v2, v1
	v_add_u32_e32 v2, v4, v2
	v_cmp_ne_u32_e32 vcc, v3, v2
	s_and_saveexec_b64 s[8:9], vcc
	s_xor_b64 s[8:9], exec, s[8:9]
	s_cbranch_execz .LBB0_165
	s_waitcnt lgkmcnt(0)
	v_mov_b32_e32 v0, 0x2000
	global_load_dword v0, v0, s[6:7] offset:1024 sc1
	s_add_u32 s14, s6, 0x2400
	s_addc_u32 s15, s7, 0
	s_waitcnt vmcnt(0)
	v_cmp_eq_u32_e32 vcc, v0, v1
	s_and_saveexec_b64 s[10:11], vcc
	s_cbranch_execz .LBB0_164
	s_add_u32 s12, s84, 0xc0200
	s_addc_u32 s13, s85, 0
	s_mov_b32 s26, 1
	s_mov_b64 s[16:17], 0
	v_mov_b32_e32 v0, 0
	s_branch .LBB0_155

; __device__ __forceinline__ unsigned xb_ld(unsigned* p)              { return __hip_atomic_load(p, __ATOMIC_RELAXED, __HIP_MEMORY_SCOPE_AGENT); }
; __device__ __forceinline__ unsigned xb_add(unsigned* p, unsigned v) { return __hip_atomic_fetch_add(p, v, __ATOMIC_RELAXED, __HIP_MEMORY_SCOPE_AGENT); }
; #define XB_SPIN(cond, bar) do { unsigned _sp = 0; while (cond) { __builtin_amdgcn_s_sleep(1); \
;     if ((++_sp & 255u) == 0u) { if (xb_ld(&(bar)[XB_TMO])) break; if (_sp > XB_SPIN_CAP) { atomicAdd(&(bar)[XB_TMO], 1u); break; } } } } while (0)
; __device__ __forceinline__ void xcd_barrier(const XcdBarrier& b) {
;     ...
;         const unsigned old = xb_add(&bar[XB_XSUB(b.x)], 1u);
;         const unsigned gen = old / nloc;
;         if (old + 1u == (gen + 1u) * nloc) {
;             __builtin_amdgcn_fence(__ATOMIC_RELEASE, "agent");
;             asm volatile("s_waitcnt vmcnt(0)" ::: "memory");
;             const unsigned og = xb_add(&bar[XB_TOP], 1u);
;             const unsigned tg = og / nx;
;             if (og + 1u == (tg + 1u) * nx) xb_add(&bar[XB_TOPGEN], 1u);
;             else XB_SPIN(xb_ld(&bar[XB_TOPGEN]) == tg, bar);
;             __builtin_amdgcn_fence(__ATOMIC_ACQUIRE, "agent");
;             xb_add(&bar[XB_XGEN(b.x)], 1u);
;             asm volatile("s_waitcnt vmcnt(0)" ::: "memory");
;         } else {
;             XB_SPIN(xb_ld(&bar[XB_XGEN(b.x)]) == gen, bar);
.LBB0_211:
	s_lshl_b32 s6, s65, 8
	v_readlane_b32 s8, v247, 16
	v_readlane_b32 s9, v247, 17
	s_add_u32 s6, s8, s6
	s_addc_u32 s7, s9, 0
	v_mov_b32_e32 v1, 0x1000
	v_mov_b32_e32 v3, 1
	global_atomic_add v3, v1, v3, s[6:7] offset:1024 sc0
	v_cvt_f32_u32_e32 v1, v2
	v_sub_u32_e32 v4, 0, v2
	v_rcp_iflag_f32_e32 v1, v1
	s_nop 0
	v_mul_f32_e32 v1, 0x4f7ffffe, v1
	v_cvt_u32_f32_e32 v1, v1
	v_mul_lo_u32 v4, v4, v1
	v_mul_hi_u32 v4, v1, v4
	v_add_u32_e32 v1, v1, v4
	s_waitcnt vmcnt(0)
	buffer_inv sc1
	v_mul_hi_u32 v1, v3, v1
	v_mul_lo_u32 v4, v1, v2
	v_sub_u32_e32 v4, v3, v4
	v_add_u32_e32 v5, 1, v1
	v_cmp_ge_u32_e32 vcc, v4, v2
	v_add_u32_e32 v3, 1, v3
	s_nop 0
	v_cndmask_b32_e32 v1, v1, v5, vcc
	v_sub_u32_e32 v5, v4, v2
	v_cndmask_b32_e32 v4, v4, v5, vcc
	v_add_u32_e32 v5, 1, v1
	v_cmp_ge_u32_e32 vcc, v4, v2
	s_nop 1
	v_cndmask_b32_e32 v1, v1, v5, vcc
	v_mul_lo_u32 v4, v2, v1
	v_add_u32_e32 v2, v4, v2
	v_cmp_ne_u32_e32 vcc, v3, v2
	s_and_saveexec_b64 s[8:9], vcc
	s_xor_b64 s[8:9], exec, s[8:9]
	s_cbranch_execz .LBB0_225
	s_waitcnt lgkmcnt(0)
	v_mov_b32_e32 v0, 0x2000
	global_load_dword v0, v0, s[6:7] offset:1024 sc1
	s_add_u32 s16, s6, 0x2400
	s_addc_u32 s17, s7, 0
	s_waitcnt vmcnt(0)
	v_cmp_eq_u32_e32 vcc, v0, v1
	s_and_saveexec_b64 s[10:11], vcc
	s_cbranch_execz .LBB0_224
	s_add_u32 s14, s84, 0xc0200
	s_addc_u32 s15, s85, 0
	s_mov_b32 s28, 1
	s_mov_b64 s[18:19], 0
	v_mov_b32_e32 v0, 0
	s_branch .LBB0_215

; __device__ __forceinline__ unsigned xb_ld(unsigned* p)              { return __hip_atomic_load(p, __ATOMIC_RELAXED, __HIP_MEMORY_SCOPE_AGENT); }
; __device__ __forceinline__ unsigned xb_add(unsigned* p, unsigned v) { return __hip_atomic_fetch_add(p, v, __ATOMIC_RELAXED, __HIP_MEMORY_SCOPE_AGENT); }
; #define XB_SPIN(cond, bar) do { unsigned _sp = 0; while (cond) { __builtin_amdgcn_s_sleep(1); \
;     if ((++_sp & 255u) == 0u) { if (xb_ld(&(bar)[XB_TMO])) break; if (_sp > XB_SPIN_CAP) { atomicAdd(&(bar)[XB_TMO], 1u); break; } } } } while (0)
; __device__ __forceinline__ void xcd_barrier(const XcdBarrier& b) {
;     ...
;         const unsigned old = xb_add(&bar[XB_XSUB(b.x)], 1u);
;         const unsigned gen = old / nloc;
;         if (old + 1u == (gen + 1u) * nloc) {
;             __builtin_amdgcn_fence(__ATOMIC_RELEASE, "agent");
;             asm volatile("s_waitcnt vmcnt(0)" ::: "memory");
;             const unsigned og = xb_add(&bar[XB_TOP], 1u);
;             const unsigned tg = og / nx;
;             if (og + 1u == (tg + 1u) * nx) xb_add(&bar[XB_TOPGEN], 1u);
;             else XB_SPIN(xb_ld(&bar[XB_TOPGEN]) == tg, bar);
;             __builtin_amdgcn_fence(__ATOMIC_ACQUIRE, "agent");
;             xb_add(&bar[XB_XGEN(b.x)], 1u);
;             asm volatile("s_waitcnt vmcnt(0)" ::: "memory");
;         } else {
;             XB_SPIN(xb_ld(&bar[XB_XGEN(b.x)]) == gen, bar);
.LBB0_346:
	s_lshl_b32 s6, s65, 8
	s_add_u32 s6, s88, s6
	s_addc_u32 s7, s89, 0
	v_mov_b32_e32 v1, 0x1000
	v_mov_b32_e32 v3, 1
	global_atomic_add v3, v1, v3, s[6:7] offset:1024 sc0
	v_cvt_f32_u32_e32 v1, v2
	v_sub_u32_e32 v4, 0, v2
	v_rcp_iflag_f32_e32 v1, v1
	s_nop 0
	v_mul_f32_e32 v1, 0x4f7ffffe, v1
	v_cvt_u32_f32_e32 v1, v1
	v_mul_lo_u32 v4, v4, v1
	v_mul_hi_u32 v4, v1, v4
	v_add_u32_e32 v1, v1, v4
	s_waitcnt vmcnt(0)
	buffer_inv sc1
	v_mul_hi_u32 v1, v3, v1
	v_mul_lo_u32 v4, v1, v2
	v_sub_u32_e32 v4, v3, v4
	v_add_u32_e32 v5, 1, v1
	v_cmp_ge_u32_e32 vcc, v4, v2
	v_add_u32_e32 v3, 1, v3
	s_nop 0
	v_cndmask_b32_e32 v1, v1, v5, vcc
	v_sub_u32_e32 v5, v4, v2
	v_cndmask_b32_e32 v4, v4, v5, vcc
	v_add_u32_e32 v5, 1, v1
	v_cmp_ge_u32_e32 vcc, v4, v2
	s_nop 1
	v_cndmask_b32_e32 v1, v1, v5, vcc
	v_mul_lo_u32 v4, v2, v1
	v_add_u32_e32 v2, v4, v2
	v_cmp_ne_u32_e32 vcc, v3, v2
	s_and_saveexec_b64 s[8:9], vcc
	s_xor_b64 s[8:9], exec, s[8:9]
	s_cbranch_execz .LBB0_360
	s_waitcnt lgkmcnt(0)
	v_mov_b32_e32 v0, 0x2000
	global_load_dword v0, v0, s[6:7] offset:1024 sc1
	s_add_u32 s20, s6, 0x2400
	s_addc_u32 s21, s7, 0
	s_waitcnt vmcnt(0)
	v_cmp_eq_u32_e32 vcc, v0, v1
	s_and_saveexec_b64 s[10:11], vcc
	s_cbranch_execz .LBB0_359
	s_add_u32 s18, s84, 0xc0200
	s_addc_u32 s19, s85, 0
	s_mov_b32 s34, 1
	s_mov_b64 s[22:23], 0
	v_mov_b32_e32 v0, 0
	s_branch .LBB0_350

; __device__ __forceinline__ unsigned xb_ld(unsigned* p)              { return __hip_atomic_load(p, __ATOMIC_RELAXED, __HIP_MEMORY_SCOPE_AGENT); }
; __device__ __forceinline__ unsigned xb_add(unsigned* p, unsigned v) { return __hip_atomic_fetch_add(p, v, __ATOMIC_RELAXED, __HIP_MEMORY_SCOPE_AGENT); }
; #define XB_SPIN(cond, bar) do { unsigned _sp = 0; while (cond) { __builtin_amdgcn_s_sleep(1); \
;     if ((++_sp & 255u) == 0u) { if (xb_ld(&(bar)[XB_TMO])) break; if (_sp > XB_SPIN_CAP) { atomicAdd(&(bar)[XB_TMO], 1u); break; } } } } while (0)
; __device__ __forceinline__ void xcd_barrier(const XcdBarrier& b) {
;     ...
;         const unsigned old = xb_add(&bar[XB_XSUB(b.x)], 1u);
;         const unsigned gen = old / nloc;
;         if (old + 1u == (gen + 1u) * nloc) {
;             __builtin_amdgcn_fence(__ATOMIC_RELEASE, "agent");
;             asm volatile("s_waitcnt vmcnt(0)" ::: "memory");
;             const unsigned og = xb_add(&bar[XB_TOP], 1u);
;             const unsigned tg = og / nx;
;             if (og + 1u == (tg + 1u) * nx) xb_add(&bar[XB_TOPGEN], 1u);
;             else XB_SPIN(xb_ld(&bar[XB_TOPGEN]) == tg, bar);
;             __builtin_amdgcn_fence(__ATOMIC_ACQUIRE, "agent");
;             xb_add(&bar[XB_XGEN(b.x)], 1u);
;             asm volatile("s_waitcnt vmcnt(0)" ::: "memory");
;         } else {
;             XB_SPIN(xb_ld(&bar[XB_XGEN(b.x)]) == gen, bar);
.LBB0_529:
	s_lshl_b32 s8, s65, 8
	s_add_u32 s8, s88, s8
	s_addc_u32 s9, s89, 0
	v_mov_b32_e32 v1, 0x1000
	v_mov_b32_e32 v3, 1
	global_atomic_add v3, v1, v3, s[8:9] offset:1024 sc0
	v_cvt_f32_u32_e32 v1, v2
	v_sub_u32_e32 v4, 0, v2
	v_rcp_iflag_f32_e32 v1, v1
	s_nop 0
	v_mul_f32_e32 v1, 0x4f7ffffe, v1
	v_cvt_u32_f32_e32 v1, v1
	v_mul_lo_u32 v4, v4, v1
	v_mul_hi_u32 v4, v1, v4
	v_add_u32_e32 v1, v1, v4
	s_waitcnt vmcnt(0)
	buffer_inv sc1
	v_mul_hi_u32 v1, v3, v1
	v_mul_lo_u32 v4, v1, v2
	v_sub_u32_e32 v4, v3, v4
	v_add_u32_e32 v5, 1, v1
	v_cmp_ge_u32_e32 vcc, v4, v2
	v_add_u32_e32 v3, 1, v3
	s_nop 0
	v_cndmask_b32_e32 v1, v1, v5, vcc
	v_sub_u32_e32 v5, v4, v2
	v_cndmask_b32_e32 v4, v4, v5, vcc
	v_add_u32_e32 v5, 1, v1
	v_cmp_ge_u32_e32 vcc, v4, v2
	s_nop 1
	v_cndmask_b32_e32 v1, v1, v5, vcc
	v_mul_lo_u32 v4, v2, v1
	v_add_u32_e32 v2, v4, v2
	v_cmp_ne_u32_e32 vcc, v3, v2
	s_and_saveexec_b64 s[10:11], vcc
	s_xor_b64 s[10:11], exec, s[10:11]
	s_cbranch_execz .LBB0_543
	s_waitcnt lgkmcnt(0)
	v_mov_b32_e32 v0, 0x2000
	global_load_dword v0, v0, s[8:9] offset:1024 sc1
	s_add_u32 s22, s8, 0x2400
	s_addc_u32 s23, s9, 0
	s_waitcnt vmcnt(0)
	v_cmp_eq_u32_e32 vcc, v0, v1
	s_and_saveexec_b64 s[18:19], vcc
	s_cbranch_execz .LBB0_542
	s_add_u32 s20, s84, 0xc0200
	s_addc_u32 s21, s85, 0
	s_mov_b32 s36, 1
	s_mov_b64 s[24:25], 0
	v_mov_b32_e32 v0, 0
	s_branch .LBB0_533

; __device__ __forceinline__ unsigned xb_ld(unsigned* p)              { return __hip_atomic_load(p, __ATOMIC_RELAXED, __HIP_MEMORY_SCOPE_AGENT); }
; __device__ __forceinline__ unsigned xb_add(unsigned* p, unsigned v) { return __hip_atomic_fetch_add(p, v, __ATOMIC_RELAXED, __HIP_MEMORY_SCOPE_AGENT); }
; #define XB_SPIN(cond, bar) do { unsigned _sp = 0; while (cond) { __builtin_amdgcn_s_sleep(1); \
;     if ((++_sp & 255u) == 0u) { if (xb_ld(&(bar)[XB_TMO])) break; if (_sp > XB_SPIN_CAP) { atomicAdd(&(bar)[XB_TMO], 1u); break; } } } } while (0)
; __device__ __forceinline__ void xcd_barrier(const XcdBarrier& b) {
;     ...
;         const unsigned old = xb_add(&bar[XB_XSUB(b.x)], 1u);
;         const unsigned gen = old / nloc;
;         if (old + 1u == (gen + 1u) * nloc) {
;             __builtin_amdgcn_fence(__ATOMIC_RELEASE, "agent");
;             asm volatile("s_waitcnt vmcnt(0)" ::: "memory");
;             const unsigned og = xb_add(&bar[XB_TOP], 1u);
;             const unsigned tg = og / nx;
;             if (og + 1u == (tg + 1u) * nx) xb_add(&bar[XB_TOPGEN], 1u);
;             else XB_SPIN(xb_ld(&bar[XB_TOPGEN]) == tg, bar);
;             __builtin_amdgcn_fence(__ATOMIC_ACQUIRE, "agent");
;             xb_add(&bar[XB_XGEN(b.x)], 1u);
;             asm volatile("s_waitcnt vmcnt(0)" ::: "memory");
;         } else {
;             XB_SPIN(xb_ld(&bar[XB_XGEN(b.x)]) == gen, bar);
.LBB0_598:
	s_lshl_b32 s6, s65, 8
	s_add_u32 s6, s88, s6
	s_addc_u32 s7, s89, 0
	v_mov_b32_e32 v1, 0x1000
	v_mov_b32_e32 v3, 1
	global_atomic_add v3, v1, v3, s[6:7] offset:1024 sc0
	v_cvt_f32_u32_e32 v1, v2
	v_sub_u32_e32 v4, 0, v2
	v_rcp_iflag_f32_e32 v1, v1
	s_nop 0
	v_mul_f32_e32 v1, 0x4f7ffffe, v1
	v_cvt_u32_f32_e32 v1, v1
	v_mul_lo_u32 v4, v4, v1
	v_mul_hi_u32 v4, v1, v4
	v_add_u32_e32 v1, v1, v4
	s_waitcnt vmcnt(0)
	buffer_inv sc1
	v_mul_hi_u32 v1, v3, v1
	v_mul_lo_u32 v4, v1, v2
	v_sub_u32_e32 v4, v3, v4
	v_add_u32_e32 v5, 1, v1
	v_cmp_ge_u32_e32 vcc, v4, v2
	v_add_u32_e32 v3, 1, v3
	s_nop 0
	v_cndmask_b32_e32 v1, v1, v5, vcc
	v_sub_u32_e32 v5, v4, v2
	v_cndmask_b32_e32 v4, v4, v5, vcc
	v_add_u32_e32 v5, 1, v1
	v_cmp_ge_u32_e32 vcc, v4, v2
	s_nop 1
	v_cndmask_b32_e32 v1, v1, v5, vcc
	v_mul_lo_u32 v4, v2, v1
	v_add_u32_e32 v2, v4, v2
	v_cmp_ne_u32_e32 vcc, v3, v2
	s_and_saveexec_b64 s[8:9], vcc
	s_xor_b64 s[8:9], exec, s[8:9]
	s_cbranch_execz .LBB0_612
	s_waitcnt lgkmcnt(0)
	v_mov_b32_e32 v0, 0x2000
	global_load_dword v0, v0, s[6:7] offset:1024 sc1
	s_add_u32 s22, s6, 0x2400
	s_addc_u32 s23, s7, 0
	s_waitcnt vmcnt(0)
	v_cmp_eq_u32_e32 vcc, v0, v1
	s_and_saveexec_b64 s[10:11], vcc
	s_cbranch_execz .LBB0_611
	s_add_u32 s20, s84, 0xc0200
	s_addc_u32 s21, s85, 0
	s_mov_b32 s36, 1
	s_mov_b64 s[24:25], 0
	v_mov_b32_e32 v0, 0
	s_branch .LBB0_602

; __device__ __forceinline__ unsigned xb_ld(unsigned* p)              { return __hip_atomic_load(p, __ATOMIC_RELAXED, __HIP_MEMORY_SCOPE_AGENT); }
; __device__ __forceinline__ unsigned xb_add(unsigned* p, unsigned v) { return __hip_atomic_fetch_add(p, v, __ATOMIC_RELAXED, __HIP_MEMORY_SCOPE_AGENT); }
; #define XB_SPIN(cond, bar) do { unsigned _sp = 0; while (cond) { __builtin_amdgcn_s_sleep(1); \
;     if ((++_sp & 255u) == 0u) { if (xb_ld(&(bar)[XB_TMO])) break; if (_sp > XB_SPIN_CAP) { atomicAdd(&(bar)[XB_TMO], 1u); break; } } } } while (0)
; __device__ __forceinline__ void xcd_barrier(const XcdBarrier& b) {
;     ...
;         const unsigned old = xb_add(&bar[XB_XSUB(b.x)], 1u);
;         const unsigned gen = old / nloc;
;         if (old + 1u == (gen + 1u) * nloc) {
;             __builtin_amdgcn_fence(__ATOMIC_RELEASE, "agent");
;             asm volatile("s_waitcnt vmcnt(0)" ::: "memory");
;             const unsigned og = xb_add(&bar[XB_TOP], 1u);
;             const unsigned tg = og / nx;
;             if (og + 1u == (tg + 1u) * nx) xb_add(&bar[XB_TOPGEN], 1u);
;             else XB_SPIN(xb_ld(&bar[XB_TOPGEN]) == tg, bar);
;             __builtin_amdgcn_fence(__ATOMIC_ACQUIRE, "agent");
;             xb_add(&bar[XB_XGEN(b.x)], 1u);
;             asm volatile("s_waitcnt vmcnt(0)" ::: "memory");
;         } else {
;             XB_SPIN(xb_ld(&bar[XB_XGEN(b.x)]) == gen, bar);
.LBB0_683:
	s_lshl_b32 s3, s65, 8
	s_add_u32 s6, s88, s3
	s_addc_u32 s7, s89, 0
	v_mov_b32_e32 v1, 0x1000
	v_mov_b32_e32 v3, 1
	global_atomic_add v3, v1, v3, s[6:7] offset:1024 sc0
	v_cvt_f32_u32_e32 v1, v2
	v_sub_u32_e32 v4, 0, v2
	v_rcp_iflag_f32_e32 v1, v1
	s_nop 0
	v_mul_f32_e32 v1, 0x4f7ffffe, v1
	v_cvt_u32_f32_e32 v1, v1
	v_mul_lo_u32 v4, v4, v1
	v_mul_hi_u32 v4, v1, v4
	v_add_u32_e32 v1, v1, v4
	s_waitcnt vmcnt(0)
	buffer_inv sc1
	v_mul_hi_u32 v1, v3, v1
	v_mul_lo_u32 v4, v1, v2
	v_sub_u32_e32 v4, v3, v4
	v_add_u32_e32 v5, 1, v1
	v_cmp_ge_u32_e32 vcc, v4, v2
	v_add_u32_e32 v3, 1, v3
	s_nop 0
	v_cndmask_b32_e32 v1, v1, v5, vcc
	v_sub_u32_e32 v5, v4, v2
	v_cndmask_b32_e32 v4, v4, v5, vcc
	v_add_u32_e32 v5, 1, v1
	v_cmp_ge_u32_e32 vcc, v4, v2
	s_nop 1
	v_cndmask_b32_e32 v1, v1, v5, vcc
	v_mul_lo_u32 v4, v2, v1
	v_add_u32_e32 v2, v4, v2
	v_cmp_ne_u32_e32 vcc, v3, v2
	s_and_saveexec_b64 s[8:9], vcc
	s_xor_b64 s[8:9], exec, s[8:9]
	s_cbranch_execz .LBB0_697
	s_waitcnt lgkmcnt(0)
	v_mov_b32_e32 v0, 0x2000
	global_load_dword v0, v0, s[6:7] offset:1024 sc1
	s_add_u32 s24, s6, 0x2400
	s_addc_u32 s25, s7, 0
	s_waitcnt vmcnt(0)
	v_cmp_eq_u32_e32 vcc, v0, v1
	s_and_saveexec_b64 s[10:11], vcc
	s_cbranch_execz .LBB0_696
	s_add_u32 s22, s84, 0xc0200
	s_addc_u32 s23, s85, 0
	s_mov_b32 s3, 1
	s_mov_b64 s[26:27], 0
	v_mov_b32_e32 v0, 0
	s_branch .LBB0_687

; __device__ __forceinline__ unsigned xb_ld(unsigned* p)              { return __hip_atomic_load(p, __ATOMIC_RELAXED, __HIP_MEMORY_SCOPE_AGENT); }
; __device__ __forceinline__ unsigned xb_add(unsigned* p, unsigned v) { return __hip_atomic_fetch_add(p, v, __ATOMIC_RELAXED, __HIP_MEMORY_SCOPE_AGENT); }
; #define XB_SPIN(cond, bar) do { unsigned _sp = 0; while (cond) { __builtin_amdgcn_s_sleep(1); \
;     if ((++_sp & 255u) == 0u) { if (xb_ld(&(bar)[XB_TMO])) break; if (_sp > XB_SPIN_CAP) { atomicAdd(&(bar)[XB_TMO], 1u); break; } } } } while (0)
; __device__ __forceinline__ void xcd_barrier(const XcdBarrier& b) {
;     ...
;         const unsigned old = xb_add(&bar[XB_XSUB(b.x)], 1u);
;         const unsigned gen = old / nloc;
;         if (old + 1u == (gen + 1u) * nloc) {
;             __builtin_amdgcn_fence(__ATOMIC_RELEASE, "agent");
;             asm volatile("s_waitcnt vmcnt(0)" ::: "memory");
;             const unsigned og = xb_add(&bar[XB_TOP], 1u);
;             const unsigned tg = og / nx;
;             if (og + 1u == (tg + 1u) * nx) xb_add(&bar[XB_TOPGEN], 1u);
;             else XB_SPIN(xb_ld(&bar[XB_TOPGEN]) == tg, bar);
;             __builtin_amdgcn_fence(__ATOMIC_ACQUIRE, "agent");
;             xb_add(&bar[XB_XGEN(b.x)], 1u);
;             asm volatile("s_waitcnt vmcnt(0)" ::: "memory");
;         } else {
;             XB_SPIN(xb_ld(&bar[XB_XGEN(b.x)]) == gen, bar);
.LBB0_907:
	s_lshl_b32 s6, s65, 8
	s_add_u32 s6, s88, s6
	s_addc_u32 s7, s89, 0
	v_mov_b32_e32 v1, 0x1000
	v_mov_b32_e32 v3, 1
	global_atomic_add v3, v1, v3, s[6:7] offset:1024 sc0
	v_cvt_f32_u32_e32 v1, v2
	v_sub_u32_e32 v4, 0, v2
	v_rcp_iflag_f32_e32 v1, v1
	s_nop 0
	v_mul_f32_e32 v1, 0x4f7ffffe, v1
	v_cvt_u32_f32_e32 v1, v1
	v_mul_lo_u32 v4, v4, v1
	v_mul_hi_u32 v4, v1, v4
	v_add_u32_e32 v1, v1, v4
	s_waitcnt vmcnt(0)
	buffer_inv sc1
	v_mul_hi_u32 v1, v3, v1
	v_mul_lo_u32 v4, v1, v2
	v_sub_u32_e32 v4, v3, v4
	v_add_u32_e32 v5, 1, v1
	v_cmp_ge_u32_e32 vcc, v4, v2
	v_add_u32_e32 v3, 1, v3
	s_nop 0
	v_cndmask_b32_e32 v1, v1, v5, vcc
	v_sub_u32_e32 v5, v4, v2
	v_cndmask_b32_e32 v4, v4, v5, vcc
	v_add_u32_e32 v5, 1, v1
	v_cmp_ge_u32_e32 vcc, v4, v2
	s_nop 1
	v_cndmask_b32_e32 v1, v1, v5, vcc
	v_mul_lo_u32 v4, v2, v1
	v_add_u32_e32 v2, v4, v2
	v_cmp_ne_u32_e32 vcc, v3, v2
	s_and_saveexec_b64 s[8:9], vcc
	s_xor_b64 s[8:9], exec, s[8:9]
	s_cbranch_execz .LBB0_921
	s_waitcnt lgkmcnt(0)
	v_mov_b32_e32 v0, 0x2000
	global_load_dword v0, v0, s[6:7] offset:1024 sc1
	s_add_u32 s26, s6, 0x2400
	s_addc_u32 s27, s7, 0
	s_waitcnt vmcnt(0)
	v_cmp_eq_u32_e32 vcc, v0, v1
	s_and_saveexec_b64 s[10:11], vcc
	s_cbranch_execz .LBB0_920
	s_add_u32 s24, s84, 0xc0200
	s_addc_u32 s25, s85, 0
	s_mov_b32 s40, 1
	s_mov_b64 s[28:29], 0
	v_mov_b32_e32 v0, 0
	s_branch .LBB0_911

; __device__ __forceinline__ unsigned xb_ld(unsigned* p)              { return __hip_atomic_load(p, __ATOMIC_RELAXED, __HIP_MEMORY_SCOPE_AGENT); }
; __device__ __forceinline__ unsigned xb_add(unsigned* p, unsigned v) { return __hip_atomic_fetch_add(p, v, __ATOMIC_RELAXED, __HIP_MEMORY_SCOPE_AGENT); }
; #define XB_SPIN(cond, bar) do { unsigned _sp = 0; while (cond) { __builtin_amdgcn_s_sleep(1); \
;     if ((++_sp & 255u) == 0u) { if (xb_ld(&(bar)[XB_TMO])) break; if (_sp > XB_SPIN_CAP) { atomicAdd(&(bar)[XB_TMO], 1u); break; } } } } while (0)
; __device__ __forceinline__ void xcd_barrier(const XcdBarrier& b) {
;     ...
;         const unsigned old = xb_add(&bar[XB_XSUB(b.x)], 1u);
;         const unsigned gen = old / nloc;
;         if (old + 1u == (gen + 1u) * nloc) {
;             __builtin_amdgcn_fence(__ATOMIC_RELEASE, "agent");
;             asm volatile("s_waitcnt vmcnt(0)" ::: "memory");
;             const unsigned og = xb_add(&bar[XB_TOP], 1u);
;             const unsigned tg = og / nx;
;             if (og + 1u == (tg + 1u) * nx) xb_add(&bar[XB_TOPGEN], 1u);
;             else XB_SPIN(xb_ld(&bar[XB_TOPGEN]) == tg, bar);
;             __builtin_amdgcn_fence(__ATOMIC_ACQUIRE, "agent");
;             xb_add(&bar[XB_XGEN(b.x)], 1u);
;             asm volatile("s_waitcnt vmcnt(0)" ::: "memory");
;         } else {
;             XB_SPIN(xb_ld(&bar[XB_XGEN(b.x)]) == gen, bar);
.LBB0_1024:
	s_lshl_b32 s6, s65, 8
	s_add_u32 s6, s88, s6
	s_addc_u32 s7, s89, 0
	v_mov_b32_e32 v1, 0x1000
	v_mov_b32_e32 v3, 1
	global_atomic_add v3, v1, v3, s[6:7] offset:1024 sc0
	v_cvt_f32_u32_e32 v1, v2
	v_sub_u32_e32 v4, 0, v2
	v_rcp_iflag_f32_e32 v1, v1
	s_nop 0
	v_mul_f32_e32 v1, 0x4f7ffffe, v1
	v_cvt_u32_f32_e32 v1, v1
	v_mul_lo_u32 v4, v4, v1
	v_mul_hi_u32 v4, v1, v4
	v_add_u32_e32 v1, v1, v4
	s_waitcnt vmcnt(0)
	buffer_inv sc1
	v_mul_hi_u32 v1, v3, v1
	v_mul_lo_u32 v4, v1, v2
	v_sub_u32_e32 v4, v3, v4
	v_add_u32_e32 v5, 1, v1
	v_cmp_ge_u32_e32 vcc, v4, v2
	v_add_u32_e32 v3, 1, v3
	s_nop 0
	v_cndmask_b32_e32 v1, v1, v5, vcc
	v_sub_u32_e32 v5, v4, v2
	v_cndmask_b32_e32 v4, v4, v5, vcc
	v_add_u32_e32 v5, 1, v1
	v_cmp_ge_u32_e32 vcc, v4, v2
	s_nop 1
	v_cndmask_b32_e32 v1, v1, v5, vcc
	v_mul_lo_u32 v4, v2, v1
	v_add_u32_e32 v2, v4, v2
	v_cmp_ne_u32_e32 vcc, v3, v2
	s_and_saveexec_b64 s[8:9], vcc
	s_xor_b64 s[8:9], exec, s[8:9]
	s_cbranch_execz .LBB0_1038
	s_waitcnt lgkmcnt(0)
	v_mov_b32_e32 v0, 0x2000
	global_load_dword v0, v0, s[6:7] offset:1024 sc1
	s_add_u32 s24, s6, 0x2400
	s_addc_u32 s25, s7, 0
	s_waitcnt vmcnt(0)
	v_cmp_eq_u32_e32 vcc, v0, v1
	s_and_saveexec_b64 s[10:11], vcc
	s_cbranch_execz .LBB0_1037
	s_add_u32 s22, s84, 0xc0200
	s_addc_u32 s23, s85, 0
	s_mov_b32 s38, 1
	s_mov_b64 s[26:27], 0
	v_mov_b32_e32 v0, 0
	s_branch .LBB0_1028

; __device__ __forceinline__ unsigned xb_ld(unsigned* p)              { return __hip_atomic_load(p, __ATOMIC_RELAXED, __HIP_MEMORY_SCOPE_AGENT); }
; __device__ __forceinline__ unsigned xb_add(unsigned* p, unsigned v) { return __hip_atomic_fetch_add(p, v, __ATOMIC_RELAXED, __HIP_MEMORY_SCOPE_AGENT); }
; #define XB_SPIN(cond, bar) do { unsigned _sp = 0; while (cond) { __builtin_amdgcn_s_sleep(1); \
;     if ((++_sp & 255u) == 0u) { if (xb_ld(&(bar)[XB_TMO])) break; if (_sp > XB_SPIN_CAP) { atomicAdd(&(bar)[XB_TMO], 1u); break; } } } } while (0)
; __device__ __forceinline__ void xcd_barrier(const XcdBarrier& b) {
;     ...
;         const unsigned old = xb_add(&bar[XB_XSUB(b.x)], 1u);
;         const unsigned gen = old / nloc;
;         if (old + 1u == (gen + 1u) * nloc) {
;             __builtin_amdgcn_fence(__ATOMIC_RELEASE, "agent");
;             asm volatile("s_waitcnt vmcnt(0)" ::: "memory");
;             const unsigned og = xb_add(&bar[XB_TOP], 1u);
;             const unsigned tg = og / nx;
;             if (og + 1u == (tg + 1u) * nx) xb_add(&bar[XB_TOPGEN], 1u);
;             else XB_SPIN(xb_ld(&bar[XB_TOPGEN]) == tg, bar);
;             __builtin_amdgcn_fence(__ATOMIC_ACQUIRE, "agent");
;             xb_add(&bar[XB_XGEN(b.x)], 1u);
;             asm volatile("s_waitcnt vmcnt(0)" ::: "memory");
;         } else {
;             XB_SPIN(xb_ld(&bar[XB_XGEN(b.x)]) == gen, bar);
.LBB0_1180:
	s_lshl_b32 s3, s65, 8
	s_add_u32 s6, s88, s3
	s_addc_u32 s7, s89, 0
	v_mov_b32_e32 v1, 0x1000
	v_mov_b32_e32 v3, 1
	global_atomic_add v3, v1, v3, s[6:7] offset:1024 sc0
	v_cvt_f32_u32_e32 v1, v2
	v_sub_u32_e32 v4, 0, v2
	v_rcp_iflag_f32_e32 v1, v1
	s_nop 0
	v_mul_f32_e32 v1, 0x4f7ffffe, v1
	v_cvt_u32_f32_e32 v1, v1
	v_mul_lo_u32 v4, v4, v1
	v_mul_hi_u32 v4, v1, v4
	v_add_u32_e32 v1, v1, v4
	s_waitcnt vmcnt(0)
	buffer_inv sc1
	v_mul_hi_u32 v1, v3, v1
	v_mul_lo_u32 v4, v1, v2
	v_sub_u32_e32 v4, v3, v4
	v_add_u32_e32 v5, 1, v1
	v_cmp_ge_u32_e32 vcc, v4, v2
	v_add_u32_e32 v3, 1, v3
	s_nop 0
	v_cndmask_b32_e32 v1, v1, v5, vcc
	v_sub_u32_e32 v5, v4, v2
	v_cndmask_b32_e32 v4, v4, v5, vcc
	v_add_u32_e32 v5, 1, v1
	v_cmp_ge_u32_e32 vcc, v4, v2
	s_nop 1
	v_cndmask_b32_e32 v1, v1, v5, vcc
	v_mul_lo_u32 v4, v2, v1
	v_add_u32_e32 v2, v4, v2
	v_cmp_ne_u32_e32 vcc, v3, v2
	s_and_saveexec_b64 s[8:9], vcc
	s_xor_b64 s[8:9], exec, s[8:9]
	s_cbranch_execz .LBB0_1194
	s_waitcnt lgkmcnt(0)
	v_mov_b32_e32 v0, 0x2000
	global_load_dword v0, v0, s[6:7] offset:1024 sc1
	s_add_u32 s14, s6, 0x2400
	s_addc_u32 s15, s7, 0
	s_waitcnt vmcnt(0)
	v_cmp_eq_u32_e32 vcc, v0, v1
	s_and_saveexec_b64 s[10:11], vcc
	s_cbranch_execz .LBB0_1193
	s_add_u32 s12, s84, 0xc0200
	s_addc_u32 s13, s85, 0
	s_mov_b32 s3, 1
	s_mov_b64 s[16:17], 0
	v_mov_b32_e32 v0, 0
	s_branch .LBB0_1184

; __device__ __forceinline__ unsigned xb_ld(unsigned* p)              { return __hip_atomic_load(p, __ATOMIC_RELAXED, __HIP_MEMORY_SCOPE_AGENT); }
; __device__ __forceinline__ unsigned xb_add(unsigned* p, unsigned v) { return __hip_atomic_fetch_add(p, v, __ATOMIC_RELAXED, __HIP_MEMORY_SCOPE_AGENT); }
; #define XB_SPIN(cond, bar) do { unsigned _sp = 0; while (cond) { __builtin_amdgcn_s_sleep(1); \
;     if ((++_sp & 255u) == 0u) { if (xb_ld(&(bar)[XB_TMO])) break; if (_sp > XB_SPIN_CAP) { atomicAdd(&(bar)[XB_TMO], 1u); break; } } } } while (0)
; __device__ __forceinline__ void xcd_barrier(const XcdBarrier& b) {
;     ...
;         const unsigned old = xb_add(&bar[XB_XSUB(b.x)], 1u);
;         const unsigned gen = old / nloc;
;         if (old + 1u == (gen + 1u) * nloc) {
;             __builtin_amdgcn_fence(__ATOMIC_RELEASE, "agent");
;             asm volatile("s_waitcnt vmcnt(0)" ::: "memory");
;             const unsigned og = xb_add(&bar[XB_TOP], 1u);
;             const unsigned tg = og / nx;
;             if (og + 1u == (tg + 1u) * nx) xb_add(&bar[XB_TOPGEN], 1u);
;             else XB_SPIN(xb_ld(&bar[XB_TOPGEN]) == tg, bar);
;             __builtin_amdgcn_fence(__ATOMIC_ACQUIRE, "agent");
;             xb_add(&bar[XB_XGEN(b.x)], 1u);
;             asm volatile("s_waitcnt vmcnt(0)" ::: "memory");
;         } else {
;             XB_SPIN(xb_ld(&bar[XB_XGEN(b.x)]) == gen, bar);
.LBB0_1255:
	s_lshl_b32 s4, s65, 8
	s_add_u32 s4, s88, s4
	s_addc_u32 s5, s89, 0
	v_mov_b32_e32 v1, 0x1000
	v_mov_b32_e32 v3, 1
	global_atomic_add v3, v1, v3, s[4:5] offset:1024 sc0
	v_cvt_f32_u32_e32 v1, v2
	v_sub_u32_e32 v4, 0, v2
	v_rcp_iflag_f32_e32 v1, v1
	s_nop 0
	v_mul_f32_e32 v1, 0x4f7ffffe, v1
	v_cvt_u32_f32_e32 v1, v1
	v_mul_lo_u32 v4, v4, v1
	v_mul_hi_u32 v4, v1, v4
	v_add_u32_e32 v1, v1, v4
	s_waitcnt vmcnt(0)
	buffer_inv sc1
	v_mul_hi_u32 v1, v3, v1
	v_mul_lo_u32 v4, v1, v2
	v_sub_u32_e32 v4, v3, v4
	v_add_u32_e32 v5, 1, v1
	v_cmp_ge_u32_e32 vcc, v4, v2
	v_add_u32_e32 v3, 1, v3
	s_nop 0
	v_cndmask_b32_e32 v1, v1, v5, vcc
	v_sub_u32_e32 v5, v4, v2
	v_cndmask_b32_e32 v4, v4, v5, vcc
	v_add_u32_e32 v5, 1, v1
	v_cmp_ge_u32_e32 vcc, v4, v2
	s_nop 1
	v_cndmask_b32_e32 v1, v1, v5, vcc
	v_mul_lo_u32 v4, v2, v1
	v_add_u32_e32 v2, v4, v2
	v_cmp_ne_u32_e32 vcc, v3, v2
	s_and_saveexec_b64 s[6:7], vcc
	s_xor_b64 s[6:7], exec, s[6:7]
	s_cbranch_execz .LBB0_1269
	s_waitcnt lgkmcnt(0)
	v_mov_b32_e32 v0, 0x2000
	global_load_dword v0, v0, s[4:5] offset:1024 sc1
	s_add_u32 s12, s4, 0x2400
	s_addc_u32 s13, s5, 0
	s_waitcnt vmcnt(0)
	v_cmp_eq_u32_e32 vcc, v0, v1
	s_and_saveexec_b64 s[8:9], vcc
	s_cbranch_execz .LBB0_1268
	s_add_u32 s10, s84, 0xc0200
	s_addc_u32 s11, s85, 0
	s_mov_b32 s24, 1
	s_mov_b64 s[14:15], 0
	v_mov_b32_e32 v0, 0
	s_branch .LBB0_1259
